# P5 final gate epilogue: write-through (sc1) stores so the P5->P6 barrier has less dirty L2 to flush (on v48)
# speedup vs baseline: 1.0052x; 1.0052x over previous
; __device__ __forceinline__ float bf_lo(unsigned u) { return __uint_as_float(u << 16); }
; __device__ __forceinline__ float bf_hi(unsigned u) { return __uint_as_float(u & 0xffff0000u); }
; __device__ __forceinline__ u32x4 pk8(const f32x4& a, const f32x4& b) { u32x4 w; w.x = pk(a[0], a[1]); w.y = pk(a[2], a[3]); w.z = pk(b[0], b[1]); w.w = pk(b[2], b[3]); return w; }
;     __device__ __forceinline__ void operator()(const f32x4 (&acc)[2][2][4][2], const pg8::Unit& u, int wr, int wc, int fr, int fq) const { if (u.job) kv(acc, u, wr, wc, fr, fq); else q(acc, u, wr, wc, fr, fq); }
;     __device__ __forceinline__ void operator()(const f32x4 (&acc)[2][2][4][2], const pg8::Unit& u, int wr, int wc, int fr, int fq) const { if (u.job) e1(acc, u, wr, wc, fr, fq); else e0(acc, u, wr, wc, fr, fq); }
;     __device__ __forceinline__ void operator()(const f32x4 (&acc)[2][2][4][2], const pg8::Unit& u, int wr, int wc, int fr, int fq) const {
;         const int row0 = u.pm * 256 + wr * 64 + fr; const int col0 = u.pn * 256 + wc * 32 + 8 * fq;
; #pragma unroll
;         for (int ai = 0; ai < 2; ++ai)
; #pragma unroll
;             for (int m = 0; m < 4; ++m)
; #pragma unroll
;                 for (int bj = 0; bj < 2; ++bj) {
;                     const size_t off = (size_t)(row0 + ai * 128 + m * 16) * 2048 + col0 + bj * 128;
;                     const u32x4 g = *(const u32x4*)(G + off);
;                     f32x4 v0 = acc[ai][bj][m][0], v1 = acc[ai][bj][m][1];
;                     v0[0] *= bf_lo(g.x); v0[1] *= bf_hi(g.x); v0[2] *= bf_lo(g.y); v0[3] *= bf_hi(g.y);
;                     v1[0] *= bf_lo(g.z); v1[1] *= bf_hi(g.z); v1[2] *= bf_lo(g.w); v1[3] *= bf_hi(g.w);
;                     if (!first) { const u32x4 p = *(const u32x4*)(Mg + off);
;                         v0[0] += bf_lo(p.x); v0[1] += bf_hi(p.x); v0[2] += bf_lo(p.y); v0[3] += bf_hi(p.y);
;                         v1[0] += bf_lo(p.z); v1[1] += bf_hi(p.z); v1[2] += bf_lo(p.w); v1[3] += bf_hi(p.w); }
;                     *(u32x4*)(Mg + off) = pk8(v0, v1);
;                 }
.LBB0_1175:
	v_lshl_add_u32 v193, s3, 8, v146
	v_lshl_or_b32 v140, s2, 8, v148
	v_lshlrev_b32_e32 v140, 1, v140
	v_lshl_add_u32 v140, v193, 12, v140
	v_add_u32_e32 v141, 0x10000, v140
	v_add_u32_e32 v142, 0x20000, v140
	v_add_u32_e32 v143, 0x30000, v140
	v_add_u32_e32 v144, 0x80000, v140
	v_add_u32_e32 v145, 0x90000, v140
	v_add_u32_e32 v182, 0xa0000, v140
	v_add_u32_e32 v183, 0xb0000, v140
	v_readlane_b32 s2, v254, 9
	v_readlane_b32 s3, v254, 10
	s_nop 15
	s_nop 3
	s_andn2_b64 vcc, exec, s[4:5]
	global_load_dwordx4 v[154:157], v140, s[84:85]
	global_load_dwordx4 v[150:153], v140, s[2:3]
	global_load_dwordx4 v[162:165], v140, s[84:85] offset:256
	global_load_dwordx4 v[158:161], v140, s[2:3] offset:256
	global_load_dwordx4 v[170:173], v141, s[84:85]
	global_load_dwordx4 v[166:169], v141, s[2:3]
	global_load_dwordx4 v[178:181], v141, s[84:85] offset:256
	global_load_dwordx4 v[174:177], v141, s[2:3] offset:256
	global_load_dwordx4 v[206:209], v142, s[84:85]
	global_load_dwordx4 v[202:205], v142, s[2:3]
	global_load_dwordx4 v[214:217], v142, s[84:85] offset:256
	global_load_dwordx4 v[210:213], v142, s[2:3] offset:256
	global_load_dwordx4 v[222:225], v143, s[84:85]
	global_load_dwordx4 v[218:221], v143, s[2:3]
	global_load_dwordx4 v[230:233], v143, s[84:85] offset:256
	global_load_dwordx4 v[226:229], v143, s[2:3] offset:256
	s_waitcnt vmcnt(14)
	v_lshlrev_b32_e32 v234, 16, v150
	v_and_b32_e32 v235, 0xffff0000, v150
	v_lshlrev_b32_e32 v236, 16, v154
	v_and_b32_e32 v237, 0xffff0000, v154
	v_fmac_f32_e32 v236, v124, v234
	v_fmac_f32_e32 v237, v125, v235
	v_cvt_pk_bf16_f32 v150, v236, v237
	v_lshlrev_b32_e32 v244, 16, v151
	v_and_b32_e32 v245, 0xffff0000, v151
	v_lshlrev_b32_e32 v246, 16, v155
	v_and_b32_e32 v247, 0xffff0000, v155
	v_fmac_f32_e32 v246, v126, v244
	v_fmac_f32_e32 v247, v127, v245
	v_cvt_pk_bf16_f32 v151, v246, v247
	v_lshlrev_b32_e32 v248, 16, v152
	v_and_b32_e32 v249, 0xffff0000, v152
	v_lshlrev_b32_e32 v250, 16, v156
	v_and_b32_e32 v251, 0xffff0000, v156
	v_fmac_f32_e32 v250, v120, v248
	v_fmac_f32_e32 v251, v121, v249
	v_cvt_pk_bf16_f32 v152, v250, v251
	v_lshlrev_b32_e32 v188, 16, v153
	v_and_b32_e32 v189, 0xffff0000, v153
	v_lshlrev_b32_e32 v190, 16, v157
	v_and_b32_e32 v191, 0xffff0000, v157
	v_fmac_f32_e32 v190, v122, v188
	v_fmac_f32_e32 v191, v123, v189
	v_cvt_pk_bf16_f32 v153, v190, v191
	global_store_dwordx4 v140, v[150:153], s[84:85] sc1
	global_load_dwordx4 v[154:157], v144, s[84:85]
	global_load_dwordx4 v[150:153], v144, s[2:3]
	s_waitcnt vmcnt(15)
	v_lshlrev_b32_e32 v234, 16, v158
	v_and_b32_e32 v235, 0xffff0000, v158
	v_lshlrev_b32_e32 v236, 16, v162
	v_and_b32_e32 v237, 0xffff0000, v162
	v_fmac_f32_e32 v236, v116, v234
	v_fmac_f32_e32 v237, v117, v235
	v_cvt_pk_bf16_f32 v158, v236, v237
	v_lshlrev_b32_e32 v244, 16, v159
	v_and_b32_e32 v245, 0xffff0000, v159
	v_lshlrev_b32_e32 v246, 16, v163
	v_and_b32_e32 v247, 0xffff0000, v163
	v_fmac_f32_e32 v246, v118, v244
	v_fmac_f32_e32 v247, v119, v245
	v_cvt_pk_bf16_f32 v159, v246, v247
	v_lshlrev_b32_e32 v248, 16, v160
	v_and_b32_e32 v249, 0xffff0000, v160
	v_lshlrev_b32_e32 v250, 16, v164
	v_and_b32_e32 v251, 0xffff0000, v164
	v_fmac_f32_e32 v250, v112, v248
	v_fmac_f32_e32 v251, v113, v249
	v_cvt_pk_bf16_f32 v160, v250, v251
	v_lshlrev_b32_e32 v188, 16, v161
	v_and_b32_e32 v189, 0xffff0000, v161
	v_lshlrev_b32_e32 v190, 16, v165
	v_and_b32_e32 v191, 0xffff0000, v165
	v_fmac_f32_e32 v190, v114, v188
	v_fmac_f32_e32 v191, v115, v189
	v_cvt_pk_bf16_f32 v161, v190, v191
	global_store_dwordx4 v140, v[158:161], s[84:85] offset:256 sc1
	global_load_dwordx4 v[162:165], v144, s[84:85] offset:256
	global_load_dwordx4 v[158:161], v144, s[2:3] offset:256
	s_waitcnt vmcnt(16)
	v_lshlrev_b32_e32 v234, 16, v166
	v_and_b32_e32 v235, 0xffff0000, v166
	v_lshlrev_b32_e32 v236, 16, v170
	v_and_b32_e32 v237, 0xffff0000, v170
	v_fmac_f32_e32 v236, v108, v234
	v_fmac_f32_e32 v237, v109, v235
	v_cvt_pk_bf16_f32 v166, v236, v237
	v_lshlrev_b32_e32 v244, 16, v167
	v_and_b32_e32 v245, 0xffff0000, v167
	v_lshlrev_b32_e32 v246, 16, v171
	v_and_b32_e32 v247, 0xffff0000, v171
	v_fmac_f32_e32 v246, v110, v244
	v_fmac_f32_e32 v247, v111, v245
	v_cvt_pk_bf16_f32 v167, v246, v247
	v_lshlrev_b32_e32 v248, 16, v168
	v_and_b32_e32 v249, 0xffff0000, v168
	v_lshlrev_b32_e32 v250, 16, v172
	v_and_b32_e32 v251, 0xffff0000, v172
	v_fmac_f32_e32 v250, v104, v248
	v_fmac_f32_e32 v251, v105, v249
	v_cvt_pk_bf16_f32 v168, v250, v251
	v_lshlrev_b32_e32 v188, 16, v169
	v_and_b32_e32 v189, 0xffff0000, v169
	v_lshlrev_b32_e32 v190, 16, v173
	v_and_b32_e32 v191, 0xffff0000, v173
	v_fmac_f32_e32 v190, v106, v188
	v_fmac_f32_e32 v191, v107, v189
	v_cvt_pk_bf16_f32 v169, v190, v191
	global_store_dwordx4 v141, v[166:169], s[84:85] sc1
	global_load_dwordx4 v[170:173], v145, s[84:85]
	global_load_dwordx4 v[166:169], v145, s[2:3]
	s_waitcnt vmcnt(17)
	v_lshlrev_b32_e32 v234, 16, v174
	v_and_b32_e32 v235, 0xffff0000, v174
	v_lshlrev_b32_e32 v236, 16, v178
	v_and_b32_e32 v237, 0xffff0000, v178
	v_fmac_f32_e32 v236, v100, v234
	v_fmac_f32_e32 v237, v101, v235
	v_cvt_pk_bf16_f32 v174, v236, v237
	v_lshlrev_b32_e32 v244, 16, v175
	v_and_b32_e32 v245, 0xffff0000, v175
	v_lshlrev_b32_e32 v246, 16, v179
	v_and_b32_e32 v247, 0xffff0000, v179
	v_fmac_f32_e32 v246, v102, v244
	v_fmac_f32_e32 v247, v103, v245
	v_cvt_pk_bf16_f32 v175, v246, v247
	v_lshlrev_b32_e32 v248, 16, v176
	v_and_b32_e32 v249, 0xffff0000, v176
	v_lshlrev_b32_e32 v250, 16, v180
	v_and_b32_e32 v251, 0xffff0000, v180
	v_fmac_f32_e32 v250, v96, v248
	v_fmac_f32_e32 v251, v97, v249
	v_cvt_pk_bf16_f32 v176, v250, v251
	v_lshlrev_b32_e32 v188, 16, v177
	v_and_b32_e32 v189, 0xffff0000, v177
	v_lshlrev_b32_e32 v190, 16, v181
	v_and_b32_e32 v191, 0xffff0000, v181
	v_fmac_f32_e32 v190, v98, v188
	v_fmac_f32_e32 v191, v99, v189
	v_cvt_pk_bf16_f32 v177, v190, v191
	global_store_dwordx4 v141, v[174:177], s[84:85] offset:256 sc1
	global_load_dwordx4 v[178:181], v145, s[84:85] offset:256
	global_load_dwordx4 v[174:177], v145, s[2:3] offset:256
	s_waitcnt vmcnt(18)
; __device__ __forceinline__ float bf_lo(unsigned u) { return __uint_as_float(u << 16); }
; __device__ __forceinline__ float bf_hi(unsigned u) { return __uint_as_float(u & 0xffff0000u); }
; __device__ __forceinline__ u32x4 pk8(const f32x4& a, const f32x4& b) { u32x4 w; w.x = pk(a[0], a[1]); w.y = pk(a[2], a[3]); w.z = pk(b[0], b[1]); w.w = pk(b[2], b[3]); return w; }
;     __device__ __forceinline__ void operator()(const f32x4 (&acc)[2][2][4][2], const pg8::Unit& u, int wr, int wc, int fr, int fq) const { if (u.job) kv(acc, u, wr, wc, fr, fq); else q(acc, u, wr, wc, fr, fq); }
;     __device__ __forceinline__ void operator()(const f32x4 (&acc)[2][2][4][2], const pg8::Unit& u, int wr, int wc, int fr, int fq) const { if (u.job) e1(acc, u, wr, wc, fr, fq); else e0(acc, u, wr, wc, fr, fq); }
;     __device__ __forceinline__ void operator()(const f32x4 (&acc)[2][2][4][2], const pg8::Unit& u, int wr, int wc, int fr, int fq) const {
;         const int row0 = u.pm * 256 + wr * 64 + fr; const int col0 = u.pn * 256 + wc * 32 + 8 * fq;
; #pragma unroll
;         for (int ai = 0; ai < 2; ++ai)
; #pragma unroll
;             for (int m = 0; m < 4; ++m)
; #pragma unroll
;                 for (int bj = 0; bj < 2; ++bj) {
;                     const size_t off = (size_t)(row0 + ai * 128 + m * 16) * 2048 + col0 + bj * 128;
;                     const u32x4 g = *(const u32x4*)(G + off);
;                     f32x4 v0 = acc[ai][bj][m][0], v1 = acc[ai][bj][m][1];
;                     v0[0] *= bf_lo(g.x); v0[1] *= bf_hi(g.x); v0[2] *= bf_lo(g.y); v0[3] *= bf_hi(g.y);
;                     v1[0] *= bf_lo(g.z); v1[1] *= bf_hi(g.z); v1[2] *= bf_lo(g.w); v1[3] *= bf_hi(g.w);
;                     if (!first) { const u32x4 p = *(const u32x4*)(Mg + off);
;                         v0[0] += bf_lo(p.x); v0[1] += bf_hi(p.x); v0[2] += bf_lo(p.y); v0[3] += bf_hi(p.y);
;                         v1[0] += bf_lo(p.z); v1[1] += bf_hi(p.z); v1[2] += bf_lo(p.w); v1[3] += bf_hi(p.w); }
;                     *(u32x4*)(Mg + off) = pk8(v0, v1);
;                 }
	v_lshlrev_b32_e32 v234, 16, v202
	v_and_b32_e32 v235, 0xffff0000, v202
	v_lshlrev_b32_e32 v236, 16, v206
	v_and_b32_e32 v237, 0xffff0000, v206
	v_fmac_f32_e32 v236, v92, v234
	v_fmac_f32_e32 v237, v93, v235
	v_cvt_pk_bf16_f32 v202, v236, v237
	v_lshlrev_b32_e32 v244, 16, v203
	v_and_b32_e32 v245, 0xffff0000, v203
	v_lshlrev_b32_e32 v246, 16, v207
	v_and_b32_e32 v247, 0xffff0000, v207
	v_fmac_f32_e32 v246, v94, v244
	v_fmac_f32_e32 v247, v95, v245
	v_cvt_pk_bf16_f32 v203, v246, v247
	v_lshlrev_b32_e32 v248, 16, v204
	v_and_b32_e32 v249, 0xffff0000, v204
	v_lshlrev_b32_e32 v250, 16, v208
	v_and_b32_e32 v251, 0xffff0000, v208
	v_fmac_f32_e32 v250, v88, v248
	v_fmac_f32_e32 v251, v89, v249
	v_cvt_pk_bf16_f32 v204, v250, v251
	v_lshlrev_b32_e32 v188, 16, v205
	v_and_b32_e32 v189, 0xffff0000, v205
	v_lshlrev_b32_e32 v190, 16, v209
	v_and_b32_e32 v191, 0xffff0000, v209
	v_fmac_f32_e32 v190, v90, v188
	v_fmac_f32_e32 v191, v91, v189
	v_cvt_pk_bf16_f32 v205, v190, v191
	global_store_dwordx4 v142, v[202:205], s[84:85] sc1
	global_load_dwordx4 v[206:209], v182, s[84:85]
	global_load_dwordx4 v[202:205], v182, s[2:3]
	s_waitcnt vmcnt(19)
	v_lshlrev_b32_e32 v234, 16, v210
	v_and_b32_e32 v235, 0xffff0000, v210
	v_lshlrev_b32_e32 v236, 16, v214
	v_and_b32_e32 v237, 0xffff0000, v214
	v_fmac_f32_e32 v236, v84, v234
	v_fmac_f32_e32 v237, v85, v235
	v_cvt_pk_bf16_f32 v210, v236, v237
	v_lshlrev_b32_e32 v244, 16, v211
	v_and_b32_e32 v245, 0xffff0000, v211
	v_lshlrev_b32_e32 v246, 16, v215
	v_and_b32_e32 v247, 0xffff0000, v215
	v_fmac_f32_e32 v246, v86, v244
	v_fmac_f32_e32 v247, v87, v245
	v_cvt_pk_bf16_f32 v211, v246, v247
	v_lshlrev_b32_e32 v248, 16, v212
	v_and_b32_e32 v249, 0xffff0000, v212
	v_lshlrev_b32_e32 v250, 16, v216
	v_and_b32_e32 v251, 0xffff0000, v216
	v_fmac_f32_e32 v250, v80, v248
	v_fmac_f32_e32 v251, v81, v249
	v_cvt_pk_bf16_f32 v212, v250, v251
	v_lshlrev_b32_e32 v188, 16, v213
	v_and_b32_e32 v189, 0xffff0000, v213
	v_lshlrev_b32_e32 v190, 16, v217
	v_and_b32_e32 v191, 0xffff0000, v217
	v_fmac_f32_e32 v190, v82, v188
	v_fmac_f32_e32 v191, v83, v189
	v_cvt_pk_bf16_f32 v213, v190, v191
	global_store_dwordx4 v142, v[210:213], s[84:85] offset:256 sc1
	global_load_dwordx4 v[214:217], v182, s[84:85] offset:256
	global_load_dwordx4 v[210:213], v182, s[2:3] offset:256
	s_waitcnt vmcnt(20)
	v_lshlrev_b32_e32 v234, 16, v218
	v_and_b32_e32 v235, 0xffff0000, v218
	v_lshlrev_b32_e32 v236, 16, v222
	v_and_b32_e32 v237, 0xffff0000, v222
	v_fmac_f32_e32 v236, v76, v234
	v_fmac_f32_e32 v237, v77, v235
	v_cvt_pk_bf16_f32 v218, v236, v237
	v_lshlrev_b32_e32 v244, 16, v219
	v_and_b32_e32 v245, 0xffff0000, v219
	v_lshlrev_b32_e32 v246, 16, v223
	v_and_b32_e32 v247, 0xffff0000, v223
	v_fmac_f32_e32 v246, v78, v244
	v_fmac_f32_e32 v247, v79, v245
	v_cvt_pk_bf16_f32 v219, v246, v247
	v_lshlrev_b32_e32 v248, 16, v220
	v_and_b32_e32 v249, 0xffff0000, v220
	v_lshlrev_b32_e32 v250, 16, v224
	v_and_b32_e32 v251, 0xffff0000, v224
	v_fmac_f32_e32 v250, v72, v248
	v_fmac_f32_e32 v251, v73, v249
	v_cvt_pk_bf16_f32 v220, v250, v251
	v_lshlrev_b32_e32 v188, 16, v221
	v_and_b32_e32 v189, 0xffff0000, v221
	v_lshlrev_b32_e32 v190, 16, v225
	v_and_b32_e32 v191, 0xffff0000, v225
	v_fmac_f32_e32 v190, v74, v188
	v_fmac_f32_e32 v191, v75, v189
	v_cvt_pk_bf16_f32 v221, v190, v191
	global_store_dwordx4 v143, v[218:221], s[84:85] sc1
	global_load_dwordx4 v[222:225], v183, s[84:85]
	global_load_dwordx4 v[218:221], v183, s[2:3]
	s_waitcnt vmcnt(21)
	v_lshlrev_b32_e32 v234, 16, v226
	v_and_b32_e32 v235, 0xffff0000, v226
	v_lshlrev_b32_e32 v236, 16, v230
	v_and_b32_e32 v237, 0xffff0000, v230
	v_fmac_f32_e32 v236, v68, v234
	v_fmac_f32_e32 v237, v69, v235
	v_cvt_pk_bf16_f32 v226, v236, v237
	v_lshlrev_b32_e32 v244, 16, v227
	v_and_b32_e32 v245, 0xffff0000, v227
	v_lshlrev_b32_e32 v246, 16, v231
	v_and_b32_e32 v247, 0xffff0000, v231
	v_fmac_f32_e32 v246, v70, v244
	v_fmac_f32_e32 v247, v71, v245
	v_cvt_pk_bf16_f32 v227, v246, v247
	v_lshlrev_b32_e32 v248, 16, v228
	v_and_b32_e32 v249, 0xffff0000, v228
	v_lshlrev_b32_e32 v250, 16, v232
	v_and_b32_e32 v251, 0xffff0000, v232
	v_fmac_f32_e32 v250, v64, v248
	v_fmac_f32_e32 v251, v65, v249
	v_cvt_pk_bf16_f32 v228, v250, v251
	v_lshlrev_b32_e32 v188, 16, v229
	v_and_b32_e32 v189, 0xffff0000, v229
	v_lshlrev_b32_e32 v190, 16, v233
	v_and_b32_e32 v191, 0xffff0000, v233
	v_fmac_f32_e32 v190, v66, v188
	v_fmac_f32_e32 v191, v67, v189
	v_cvt_pk_bf16_f32 v229, v190, v191
	global_store_dwordx4 v143, v[226:229], s[84:85] offset:256 sc1
	global_load_dwordx4 v[230:233], v183, s[84:85] offset:256
	global_load_dwordx4 v[226:229], v183, s[2:3] offset:256
	s_waitcnt vmcnt(21)
	v_lshlrev_b32_e32 v234, 16, v150
	v_and_b32_e32 v235, 0xffff0000, v150
	v_lshlrev_b32_e32 v236, 16, v154
	v_and_b32_e32 v237, 0xffff0000, v154
	v_fmac_f32_e32 v236, v60, v234
	v_fmac_f32_e32 v237, v61, v235
	v_cvt_pk_bf16_f32 v150, v236, v237
	v_lshlrev_b32_e32 v244, 16, v151
	v_and_b32_e32 v245, 0xffff0000, v151
	v_lshlrev_b32_e32 v246, 16, v155
	v_and_b32_e32 v247, 0xffff0000, v155
	v_fmac_f32_e32 v246, v62, v244
	v_fmac_f32_e32 v247, v63, v245
	v_cvt_pk_bf16_f32 v151, v246, v247
	v_lshlrev_b32_e32 v248, 16, v152
	v_and_b32_e32 v249, 0xffff0000, v152
	v_lshlrev_b32_e32 v250, 16, v156
	v_and_b32_e32 v251, 0xffff0000, v156
	v_fmac_f32_e32 v250, v56, v248
	v_fmac_f32_e32 v251, v57, v249
	v_cvt_pk_bf16_f32 v152, v250, v251
	v_lshlrev_b32_e32 v188, 16, v153
	v_and_b32_e32 v189, 0xffff0000, v153
	v_lshlrev_b32_e32 v190, 16, v157
	v_and_b32_e32 v191, 0xffff0000, v157
	v_fmac_f32_e32 v190, v58, v188
	v_fmac_f32_e32 v191, v59, v189
	v_cvt_pk_bf16_f32 v153, v190, v191
	global_store_dwordx4 v144, v[150:153], s[84:85] sc1
	s_waitcnt vmcnt(19)
; __device__ __forceinline__ float bf_lo(unsigned u) { return __uint_as_float(u << 16); }
; __device__ __forceinline__ float bf_hi(unsigned u) { return __uint_as_float(u & 0xffff0000u); }
; __device__ __forceinline__ u32x4 pk8(const f32x4& a, const f32x4& b) { u32x4 w; w.x = pk(a[0], a[1]); w.y = pk(a[2], a[3]); w.z = pk(b[0], b[1]); w.w = pk(b[2], b[3]); return w; }
;     __device__ __forceinline__ void operator()(const f32x4 (&acc)[2][2][4][2], const pg8::Unit& u, int wr, int wc, int fr, int fq) const { if (u.job) kv(acc, u, wr, wc, fr, fq); else q(acc, u, wr, wc, fr, fq); }
;     __device__ __forceinline__ void operator()(const f32x4 (&acc)[2][2][4][2], const pg8::Unit& u, int wr, int wc, int fr, int fq) const { if (u.job) e1(acc, u, wr, wc, fr, fq); else e0(acc, u, wr, wc, fr, fq); }
;     __device__ __forceinline__ void operator()(const f32x4 (&acc)[2][2][4][2], const pg8::Unit& u, int wr, int wc, int fr, int fq) const {
;         const int row0 = u.pm * 256 + wr * 64 + fr; const int col0 = u.pn * 256 + wc * 32 + 8 * fq;
; #pragma unroll
;         for (int ai = 0; ai < 2; ++ai)
; #pragma unroll
;             for (int m = 0; m < 4; ++m)
; #pragma unroll
;                 for (int bj = 0; bj < 2; ++bj) {
;                     const size_t off = (size_t)(row0 + ai * 128 + m * 16) * 2048 + col0 + bj * 128;
;                     const u32x4 g = *(const u32x4*)(G + off);
;                     f32x4 v0 = acc[ai][bj][m][0], v1 = acc[ai][bj][m][1];
;                     v0[0] *= bf_lo(g.x); v0[1] *= bf_hi(g.x); v0[2] *= bf_lo(g.y); v0[3] *= bf_hi(g.y);
;                     v1[0] *= bf_lo(g.z); v1[1] *= bf_hi(g.z); v1[2] *= bf_lo(g.w); v1[3] *= bf_hi(g.w);
;                     if (!first) { const u32x4 p = *(const u32x4*)(Mg + off);
;                         v0[0] += bf_lo(p.x); v0[1] += bf_hi(p.x); v0[2] += bf_lo(p.y); v0[3] += bf_hi(p.y);
;                         v1[0] += bf_lo(p.z); v1[1] += bf_hi(p.z); v1[2] += bf_lo(p.w); v1[3] += bf_hi(p.w); }
;                     *(u32x4*)(Mg + off) = pk8(v0, v1);
;                 }
	v_lshlrev_b32_e32 v234, 16, v158
	v_and_b32_e32 v235, 0xffff0000, v158
	v_lshlrev_b32_e32 v236, 16, v162
	v_and_b32_e32 v237, 0xffff0000, v162
	v_fmac_f32_e32 v236, v52, v234
	v_fmac_f32_e32 v237, v53, v235
	v_cvt_pk_bf16_f32 v158, v236, v237
	v_lshlrev_b32_e32 v244, 16, v159
	v_and_b32_e32 v245, 0xffff0000, v159
	v_lshlrev_b32_e32 v246, 16, v163
	v_and_b32_e32 v247, 0xffff0000, v163
	v_fmac_f32_e32 v246, v54, v244
	v_fmac_f32_e32 v247, v55, v245
	v_cvt_pk_bf16_f32 v159, v246, v247
	v_lshlrev_b32_e32 v248, 16, v160
	v_and_b32_e32 v249, 0xffff0000, v160
	v_lshlrev_b32_e32 v250, 16, v164
	v_and_b32_e32 v251, 0xffff0000, v164
	v_fmac_f32_e32 v250, v48, v248
	v_fmac_f32_e32 v251, v49, v249
	v_cvt_pk_bf16_f32 v160, v250, v251
	v_lshlrev_b32_e32 v188, 16, v161
	v_and_b32_e32 v189, 0xffff0000, v161
	v_lshlrev_b32_e32 v190, 16, v165
	v_and_b32_e32 v191, 0xffff0000, v165
	v_fmac_f32_e32 v190, v50, v188
	v_fmac_f32_e32 v191, v51, v189
	v_cvt_pk_bf16_f32 v161, v190, v191
	global_store_dwordx4 v144, v[158:161], s[84:85] offset:256 sc1
	s_waitcnt vmcnt(17)
	v_lshlrev_b32_e32 v234, 16, v166
	v_and_b32_e32 v235, 0xffff0000, v166
	v_lshlrev_b32_e32 v236, 16, v170
	v_and_b32_e32 v237, 0xffff0000, v170
	v_fmac_f32_e32 v236, v44, v234
	v_fmac_f32_e32 v237, v45, v235
	v_cvt_pk_bf16_f32 v166, v236, v237
	v_lshlrev_b32_e32 v244, 16, v167
	v_and_b32_e32 v245, 0xffff0000, v167
	v_lshlrev_b32_e32 v246, 16, v171
	v_and_b32_e32 v247, 0xffff0000, v171
	v_fmac_f32_e32 v246, v46, v244
	v_fmac_f32_e32 v247, v47, v245
	v_cvt_pk_bf16_f32 v167, v246, v247
	v_lshlrev_b32_e32 v248, 16, v168
	v_and_b32_e32 v249, 0xffff0000, v168
	v_lshlrev_b32_e32 v250, 16, v172
	v_and_b32_e32 v251, 0xffff0000, v172
	v_fmac_f32_e32 v250, v40, v248
	v_fmac_f32_e32 v251, v41, v249
	v_cvt_pk_bf16_f32 v168, v250, v251
	v_lshlrev_b32_e32 v188, 16, v169
	v_and_b32_e32 v189, 0xffff0000, v169
	v_lshlrev_b32_e32 v190, 16, v173
	v_and_b32_e32 v191, 0xffff0000, v173
	v_fmac_f32_e32 v190, v42, v188
	v_fmac_f32_e32 v191, v43, v189
	v_cvt_pk_bf16_f32 v169, v190, v191
	global_store_dwordx4 v145, v[166:169], s[84:85] sc1
	s_waitcnt vmcnt(15)
	v_lshlrev_b32_e32 v234, 16, v174
	v_and_b32_e32 v235, 0xffff0000, v174
	v_lshlrev_b32_e32 v236, 16, v178
	v_and_b32_e32 v237, 0xffff0000, v178
	v_fmac_f32_e32 v236, v36, v234
	v_fmac_f32_e32 v237, v37, v235
	v_cvt_pk_bf16_f32 v174, v236, v237
	v_lshlrev_b32_e32 v244, 16, v175
	v_and_b32_e32 v245, 0xffff0000, v175
	v_lshlrev_b32_e32 v246, 16, v179
	v_and_b32_e32 v247, 0xffff0000, v179
	v_fmac_f32_e32 v246, v38, v244
	v_fmac_f32_e32 v247, v39, v245
	v_cvt_pk_bf16_f32 v175, v246, v247
	v_lshlrev_b32_e32 v248, 16, v176
	v_and_b32_e32 v249, 0xffff0000, v176
	v_lshlrev_b32_e32 v250, 16, v180
	v_and_b32_e32 v251, 0xffff0000, v180
	v_fmac_f32_e32 v250, v32, v248
	v_fmac_f32_e32 v251, v33, v249
	v_cvt_pk_bf16_f32 v176, v250, v251
	v_lshlrev_b32_e32 v188, 16, v177
	v_and_b32_e32 v189, 0xffff0000, v177
	v_lshlrev_b32_e32 v190, 16, v181
	v_and_b32_e32 v191, 0xffff0000, v181
	v_fmac_f32_e32 v190, v34, v188
	v_fmac_f32_e32 v191, v35, v189
	v_cvt_pk_bf16_f32 v177, v190, v191
	global_store_dwordx4 v145, v[174:177], s[84:85] offset:256 sc1
	s_waitcnt vmcnt(13)
	v_lshlrev_b32_e32 v234, 16, v202
	v_and_b32_e32 v235, 0xffff0000, v202
	v_lshlrev_b32_e32 v236, 16, v206
	v_and_b32_e32 v237, 0xffff0000, v206
	v_fmac_f32_e32 v236, v28, v234
	v_fmac_f32_e32 v237, v29, v235
	v_cvt_pk_bf16_f32 v202, v236, v237
	v_lshlrev_b32_e32 v244, 16, v203
	v_and_b32_e32 v245, 0xffff0000, v203
	v_lshlrev_b32_e32 v246, 16, v207
	v_and_b32_e32 v247, 0xffff0000, v207
	v_fmac_f32_e32 v246, v30, v244
	v_fmac_f32_e32 v247, v31, v245
	v_cvt_pk_bf16_f32 v203, v246, v247
	v_lshlrev_b32_e32 v248, 16, v204
	v_and_b32_e32 v249, 0xffff0000, v204
	v_lshlrev_b32_e32 v250, 16, v208
	v_and_b32_e32 v251, 0xffff0000, v208
	v_fmac_f32_e32 v250, v24, v248
	v_fmac_f32_e32 v251, v25, v249
	v_cvt_pk_bf16_f32 v204, v250, v251
	v_lshlrev_b32_e32 v188, 16, v205
	v_and_b32_e32 v189, 0xffff0000, v205
	v_lshlrev_b32_e32 v190, 16, v209
	v_and_b32_e32 v191, 0xffff0000, v209
	v_fmac_f32_e32 v190, v26, v188
	v_fmac_f32_e32 v191, v27, v189
	v_cvt_pk_bf16_f32 v205, v190, v191
	global_store_dwordx4 v182, v[202:205], s[84:85] sc1
	s_waitcnt vmcnt(11)
; __device__ __forceinline__ float bf_lo(unsigned u) { return __uint_as_float(u << 16); }
; __device__ __forceinline__ float bf_hi(unsigned u) { return __uint_as_float(u & 0xffff0000u); }
; __device__ __forceinline__ u32x4 pk8(const f32x4& a, const f32x4& b) { u32x4 w; w.x = pk(a[0], a[1]); w.y = pk(a[2], a[3]); w.z = pk(b[0], b[1]); w.w = pk(b[2], b[3]); return w; }
;     __device__ __forceinline__ void operator()(const f32x4 (&acc)[2][2][4][2], const pg8::Unit& u, int wr, int wc, int fr, int fq) const { if (u.job) kv(acc, u, wr, wc, fr, fq); else q(acc, u, wr, wc, fr, fq); }
;     __device__ __forceinline__ void operator()(const f32x4 (&acc)[2][2][4][2], const pg8::Unit& u, int wr, int wc, int fr, int fq) const { if (u.job) e1(acc, u, wr, wc, fr, fq); else e0(acc, u, wr, wc, fr, fq); }
;     __device__ __forceinline__ void operator()(const f32x4 (&acc)[2][2][4][2], const pg8::Unit& u, int wr, int wc, int fr, int fq) const {
;         const int row0 = u.pm * 256 + wr * 64 + fr; const int col0 = u.pn * 256 + wc * 32 + 8 * fq;
; #pragma unroll
;         for (int ai = 0; ai < 2; ++ai)
; #pragma unroll
;             for (int m = 0; m < 4; ++m)
; #pragma unroll
;                 for (int bj = 0; bj < 2; ++bj) {
;                     const size_t off = (size_t)(row0 + ai * 128 + m * 16) * 2048 + col0 + bj * 128;
;                     const u32x4 g = *(const u32x4*)(G + off);
;                     f32x4 v0 = acc[ai][bj][m][0], v1 = acc[ai][bj][m][1];
;                     v0[0] *= bf_lo(g.x); v0[1] *= bf_hi(g.x); v0[2] *= bf_lo(g.y); v0[3] *= bf_hi(g.y);
;                     v1[0] *= bf_lo(g.z); v1[1] *= bf_hi(g.z); v1[2] *= bf_lo(g.w); v1[3] *= bf_hi(g.w);
;                     if (!first) { const u32x4 p = *(const u32x4*)(Mg + off);
;                         v0[0] += bf_lo(p.x); v0[1] += bf_hi(p.x); v0[2] += bf_lo(p.y); v0[3] += bf_hi(p.y);
;                         v1[0] += bf_lo(p.z); v1[1] += bf_hi(p.z); v1[2] += bf_lo(p.w); v1[3] += bf_hi(p.w); }
;                     *(u32x4*)(Mg + off) = pk8(v0, v1);
;                 }
	v_lshlrev_b32_e32 v234, 16, v210
	v_and_b32_e32 v235, 0xffff0000, v210
	v_lshlrev_b32_e32 v236, 16, v214
	v_and_b32_e32 v237, 0xffff0000, v214
	v_fmac_f32_e32 v236, v20, v234
	v_fmac_f32_e32 v237, v21, v235
	v_cvt_pk_bf16_f32 v210, v236, v237
	v_lshlrev_b32_e32 v244, 16, v211
	v_and_b32_e32 v245, 0xffff0000, v211
	v_lshlrev_b32_e32 v246, 16, v215
	v_and_b32_e32 v247, 0xffff0000, v215
	v_fmac_f32_e32 v246, v22, v244
	v_fmac_f32_e32 v247, v23, v245
	v_cvt_pk_bf16_f32 v211, v246, v247
	v_lshlrev_b32_e32 v248, 16, v212
	v_and_b32_e32 v249, 0xffff0000, v212
	v_lshlrev_b32_e32 v250, 16, v216
	v_and_b32_e32 v251, 0xffff0000, v216
	v_fmac_f32_e32 v250, v16, v248
	v_fmac_f32_e32 v251, v17, v249
	v_cvt_pk_bf16_f32 v212, v250, v251
	v_lshlrev_b32_e32 v188, 16, v213
	v_and_b32_e32 v189, 0xffff0000, v213
	v_lshlrev_b32_e32 v190, 16, v217
	v_and_b32_e32 v191, 0xffff0000, v217
	v_fmac_f32_e32 v190, v18, v188
	v_fmac_f32_e32 v191, v19, v189
	v_cvt_pk_bf16_f32 v213, v190, v191
	global_store_dwordx4 v182, v[210:213], s[84:85] offset:256 sc1
	s_waitcnt vmcnt(9)
	v_lshlrev_b32_e32 v234, 16, v218
	v_and_b32_e32 v235, 0xffff0000, v218
	v_lshlrev_b32_e32 v236, 16, v222
	v_and_b32_e32 v237, 0xffff0000, v222
	v_fmac_f32_e32 v236, v12, v234
	v_fmac_f32_e32 v237, v13, v235
	v_cvt_pk_bf16_f32 v218, v236, v237
	v_lshlrev_b32_e32 v244, 16, v219
	v_and_b32_e32 v245, 0xffff0000, v219
	v_lshlrev_b32_e32 v246, 16, v223
	v_and_b32_e32 v247, 0xffff0000, v223
	v_fmac_f32_e32 v246, v14, v244
	v_fmac_f32_e32 v247, v15, v245
	v_cvt_pk_bf16_f32 v219, v246, v247
	v_lshlrev_b32_e32 v248, 16, v220
	v_and_b32_e32 v249, 0xffff0000, v220
	v_lshlrev_b32_e32 v250, 16, v224
	v_and_b32_e32 v251, 0xffff0000, v224
	v_fmac_f32_e32 v250, v8, v248
	v_fmac_f32_e32 v251, v9, v249
	v_cvt_pk_bf16_f32 v220, v250, v251
	v_lshlrev_b32_e32 v188, 16, v221
	v_and_b32_e32 v189, 0xffff0000, v221
	v_lshlrev_b32_e32 v190, 16, v225
	v_and_b32_e32 v191, 0xffff0000, v225
	v_fmac_f32_e32 v190, v10, v188
	v_fmac_f32_e32 v191, v11, v189
	v_cvt_pk_bf16_f32 v221, v190, v191
	global_store_dwordx4 v183, v[218:221], s[84:85] sc1
	s_waitcnt vmcnt(7)
	v_lshlrev_b32_e32 v234, 16, v226
	v_and_b32_e32 v235, 0xffff0000, v226
	v_lshlrev_b32_e32 v236, 16, v230
	v_and_b32_e32 v237, 0xffff0000, v230
	v_fmac_f32_e32 v236, v4, v234
	v_fmac_f32_e32 v237, v5, v235
	v_cvt_pk_bf16_f32 v226, v236, v237
	v_lshlrev_b32_e32 v244, 16, v227
	v_and_b32_e32 v245, 0xffff0000, v227
	v_lshlrev_b32_e32 v246, 16, v231
	v_and_b32_e32 v247, 0xffff0000, v231
	v_fmac_f32_e32 v246, v6, v244
	v_fmac_f32_e32 v247, v7, v245
	v_cvt_pk_bf16_f32 v227, v246, v247
	v_lshlrev_b32_e32 v248, 16, v228
	v_and_b32_e32 v249, 0xffff0000, v228
	v_lshlrev_b32_e32 v250, 16, v232
	v_and_b32_e32 v251, 0xffff0000, v232
	v_fmac_f32_e32 v250, v0, v248
	v_fmac_f32_e32 v251, v1, v249
	v_cvt_pk_bf16_f32 v228, v250, v251
	v_lshlrev_b32_e32 v188, 16, v229
	v_and_b32_e32 v189, 0xffff0000, v229
	v_lshlrev_b32_e32 v190, 16, v233
	v_and_b32_e32 v191, 0xffff0000, v233
	v_fmac_f32_e32 v190, v2, v188
	v_fmac_f32_e32 v191, v3, v189
	v_cvt_pk_bf16_f32 v229, v190, v191
	global_store_dwordx4 v183, v[226:229], s[84:85] offset:256 sc1
	s_mov_b64 s[34:35], -1
	s_cbranch_vccnz .LBB0_1164
	s_andn2_b64 vcc, exec, s[8:9]
	s_cbranch_vccnz .LBB0_1163
	s_barrier
	s_branch .LBB0_1163
